# grid barrier: all waiters poll the arrival counter against (gen+1)*n_xcd (no generation-word hop); first-barrier census loads issued together
# baseline (speedup 1.0000x reference)
.LBB0_858:
	s_mov_b64 s[4:5], -1
	s_waitcnt lgkmcnt(0)
	v_readlane_b32 s2, v253, 30
	v_readlane_b32 s3, v253, 31
	s_nop 4
	global_load_dword v0, v2, s[2:3] sc1
	v_readlane_b32 s2, v253, 32
	v_readlane_b32 s3, v253, 33
	s_nop 4
	global_load_dword v1, v2, s[2:3] sc1
	v_readlane_b32 s2, v253, 34
	v_readlane_b32 s3, v253, 35
	s_nop 4
	global_load_dword v3, v2, s[2:3] sc1
	v_readlane_b32 s2, v253, 36
	v_readlane_b32 s3, v253, 37
	s_nop 4
	global_load_dword v4, v2, s[2:3] sc1
	v_readlane_b32 s2, v253, 38
	v_readlane_b32 s3, v253, 39
	s_nop 4
	global_load_dword v5, v2, s[2:3] sc1
	v_readlane_b32 s2, v253, 40
	v_readlane_b32 s3, v253, 41
	s_nop 4
	global_load_dword v6, v2, s[2:3] sc1
	v_readlane_b32 s2, v253, 42
	v_readlane_b32 s3, v253, 43
	s_nop 4
	global_load_dword v7, v2, s[2:3] sc1
	v_readlane_b32 s2, v253, 44
	v_readlane_b32 s3, v253, 45
	s_nop 4
	global_load_dword v8, v2, s[2:3] sc1
	v_readlane_b32 s2, v253, 46
	v_readlane_b32 s3, v253, 47
	s_nop 4
	global_load_dword v9, v2, s[2:3] sc1
	v_readlane_b32 s2, v253, 48
	v_readlane_b32 s3, v253, 49
	s_nop 4
	global_load_dword v10, v2, s[2:3] sc1
	v_readlane_b32 s2, v253, 50
	v_readlane_b32 s3, v253, 51
	s_nop 4
	global_load_dword v11, v2, s[2:3] sc1
	v_readlane_b32 s2, v253, 52
	v_readlane_b32 s3, v253, 53
	s_nop 4
	global_load_dword v12, v2, s[2:3] sc1
	v_readlane_b32 s2, v253, 54
	v_readlane_b32 s3, v253, 55
	s_nop 4
	global_load_dword v13, v2, s[2:3] sc1
	v_readlane_b32 s2, v253, 56
	v_readlane_b32 s3, v253, 57
	s_nop 4
	global_load_dword v14, v2, s[2:3] sc1
	v_readlane_b32 s2, v253, 58
	v_readlane_b32 s3, v253, 59
	s_nop 4
	global_load_dword v15, v2, s[2:3] sc1
	v_readlane_b32 s2, v253, 60
	v_readlane_b32 s3, v253, 61
	s_nop 4
	global_load_dword v16, v2, s[2:3] sc1
	s_mov_b64 s[2:3], -1
	s_waitcnt vmcnt(0)
	v_add_u32_e32 v17, v1, v0
	v_add_u32_e32 v17, v17, v3
	v_add_u32_e32 v17, v17, v4
	v_add_u32_e32 v17, v17, v5
	v_add_u32_e32 v17, v17, v6
	v_add_u32_e32 v17, v17, v7
	v_add_u32_e32 v17, v17, v8
	v_add_u32_e32 v17, v17, v9
	v_add_u32_e32 v17, v17, v10
	v_add_u32_e32 v17, v17, v11
	v_add_u32_e32 v17, v17, v12
	v_add_u32_e32 v17, v17, v13
	v_add_u32_e32 v17, v17, v14
	v_add_u32_e32 v17, v17, v15
	v_add_u32_e32 v17, v17, v16
	v_cmp_eq_u32_e32 vcc, s27, v17
	s_cbranch_vccnz .LBB0_857
	s_and_b32 s2, s8, 0xff
	s_cmp_eq_u32 s2, 0
	s_mov_b64 s[2:3], -1
	s_mov_b64 s[6:7], -1
	s_sleep 1
	s_cbranch_scc1 .LBB0_862
	s_and_b64 vcc, exec, s[6:7]
	s_cbranch_vccz .LBB0_857

.LBB0_873:
	s_or_b64 exec, exec, s[2:3]
	v_cvt_f32_u32_e32 v5, v3
	s_waitcnt vmcnt(0)
	v_readfirstlane_b32 s2, v4
	v_sub_u32_e32 v4, 0, v3
	v_rcp_iflag_f32_e32 v5, v5
	v_add_u32_e32 v6, s2, v1
	v_mul_f32_e32 v5, 0x4f7ffffe, v5
	v_cvt_u32_f32_e32 v5, v5
	v_mul_lo_u32 v1, v4, v5
	v_mul_hi_u32 v1, v5, v1
	v_add_u32_e32 v1, v5, v1
	v_mul_hi_u32 v1, v6, v1
	v_mul_lo_u32 v4, v1, v3
	v_sub_u32_e32 v4, v6, v4
	v_add_u32_e32 v5, 1, v1
	v_cmp_ge_u32_e32 vcc, v4, v3
	s_nop 1
	v_cndmask_b32_e32 v1, v1, v5, vcc
	v_sub_u32_e32 v5, v4, v3
	v_cndmask_b32_e32 v4, v4, v5, vcc
	v_add_u32_e32 v5, 1, v1
	v_cmp_ge_u32_e32 vcc, v4, v3
	v_add_u32_e32 v4, 1, v6
	s_nop 0
	v_cndmask_b32_e32 v1, v1, v5, vcc
	v_mul_lo_u32 v5, v3, v1
	v_add_u32_e32 v3, v5, v3
	v_cmp_ne_u32_e32 vcc, v4, v3
	s_and_saveexec_b64 s[2:3], vcc
	s_xor_b64 s[2:3], exec, s[2:3]
	s_cbranch_execz .LBB0_887
	v_readlane_b32 s4, v254, 34
	v_readlane_b32 s5, v254, 35
	s_waitcnt lgkmcnt(0)
	v_mad_u32_u24 v1, v1, v0, v0
	s_nop 3
	global_load_dword v0, v2, s[4:5] sc1
	s_waitcnt vmcnt(0)
	v_cmp_lt_u32_e32 vcc, v0, v1
	s_and_saveexec_b64 s[4:5], vcc
	s_cbranch_execz .LBB0_886
	s_mov_b32 s16, 1
	s_mov_b64 s[6:7], 0
	s_branch .LBB0_877

.LBB0_879:
	v_readlane_b32 s10, v254, 34
	v_readlane_b32 s11, v254, 35
	s_add_i32 s16, s16, 1
	s_mov_b64 s[12:13], -1
	s_nop 2
	global_load_dword v0, v2, s[10:11] sc1
	s_waitcnt vmcnt(0)
	v_cmp_ge_u32_e32 vcc, v0, v1
	s_orn2_b64 s[10:11], vcc, exec
	s_branch .LBB0_876

.LBB0_890:
	s_or_b64 exec, exec, s[4:5]
	s_waitcnt vmcnt(0)
	v_readfirstlane_b32 s2, v3
	v_cvt_f32_u32_e32 v3, v0
	v_sub_u32_e32 v4, 0, v0
	v_add_u32_e32 v1, s2, v1
	v_readlane_b32 s2, v254, 36
	v_rcp_iflag_f32_e32 v3, v3
	v_readlane_b32 s3, v254, 37
	s_mov_b64 s[4:5], -1
	v_mul_f32_e32 v3, 0x4f7ffffe, v3
	v_cvt_u32_f32_e32 v3, v3
	v_mul_lo_u32 v4, v4, v3
	v_mul_hi_u32 v4, v3, v4
	v_add_u32_e32 v3, v3, v4
	v_mul_hi_u32 v3, v1, v3
	v_mul_lo_u32 v4, v3, v0
	v_sub_u32_e32 v4, v1, v4
	v_cmp_ge_u32_e32 vcc, v4, v0
	v_add_u32_e32 v5, 1, v3
	v_add_u32_e32 v1, 1, v1
	v_cndmask_b32_e32 v3, v3, v5, vcc
	v_sub_u32_e32 v5, v4, v0
	v_cndmask_b32_e32 v4, v4, v5, vcc
	v_cmp_ge_u32_e32 vcc, v4, v0
	v_add_u32_e32 v4, 1, v3
	s_nop 0
	v_cndmask_b32_e32 v3, v3, v4, vcc
	v_mul_lo_u32 v4, v0, v3
	v_add_u32_e32 v0, v4, v0
	v_cmp_ne_u32_e32 vcc, v1, v0
	v_mov_b32_e32 v5, v0
	v_mov_b64_e32 v[0:1], s[2:3]
	s_and_saveexec_b64 s[2:3], vcc
	s_cbranch_execz .LBB0_902
	v_readlane_b32 s4, v254, 34
	v_readlane_b32 s5, v254, 35
	s_mov_b64 s[6:7], 0
	s_nop 3
	global_load_dword v0, v2, s[4:5] sc1
	s_waitcnt vmcnt(0)
	v_cmp_lt_u32_e32 vcc, v0, v5
	s_and_saveexec_b64 s[4:5], vcc
	s_cbranch_execz .LBB0_901
	s_mov_b32 s16, 1
	s_branch .LBB0_894

.LBB0_896:
	v_readlane_b32 s10, v254, 34
	v_readlane_b32 s11, v254, 35
	s_add_i32 s16, s16, 1
	s_mov_b64 s[12:13], -1
	s_nop 2
	global_load_dword v0, v2, s[10:11] sc1
	s_waitcnt vmcnt(0)
	v_cmp_ge_u32_e32 vcc, v0, v5
	s_orn2_b64 s[10:11], vcc, exec
	s_branch .LBB0_893
